# s5 chunk-carry scan spread over 4 workgroups (256 states each) with their idle waves streaming the inputs; prep workgroups start at 36
# speedup vs baseline: 1.0115x; 1.0055x over previous
.LBB0_105:
	s_or_b64 exec, exec, s[8:9]
	s_cmpk_lt_i32 s2, 0x2c0
	s_cselect_b64 s[0:1], -1, 0
	v_writelane_b32 v254, s0, 1
	s_ashr_i32 s3, s2, 31
	s_ashr_i32 s35, s34, 31
	v_writelane_b32 v254, s1, 2
	s_lshr_b32 s0, s3, 29
	s_add_i32 s0, s2, s0
	s_ashr_i32 s6, s0, 3
	s_and_b32 s0, s0, -8
	s_sub_i32 s0, s2, s0
	s_cmpk_lt_i32 s2, 0x200
	s_mul_i32 s76, s5, s4
	s_cselect_b64 s[4:5], -1, 0
	v_writelane_b32 v254, s4, 3
	s_cmpk_lt_i32 s2, 0x100
	s_movk_i32 s91, 0x59
	v_writelane_b32 v254, s5, 4
	s_cselect_b64 s[4:5], -1, 0
	v_writelane_b32 v254, s4, 5
	s_cmp_gt_i32 s2, 31
	s_mul_i32 s7, s0, 33
	v_writelane_b32 v254, s5, 6
	s_cselect_b64 s[4:5], -1, 0
	v_writelane_b32 v254, s4, 7
	s_movk_i32 s90, 0x400
	v_add_u32_e32 v0, 64, v31
	v_writelane_b32 v254, s5, 8
	v_cmp_lt_i32_e32 vcc, v30, v0
	v_readlane_b32 s1, v254, 0
	s_addk_i32 s1, 0xc000
	s_cmp_gt_i32 s2, 35
	v_writelane_b32 v254, s1, 9
	s_cselect_b64 s[4:5], -1, 0
	v_writelane_b32 v254, s4, 10
	s_add_i32 s1, s33, 0xfffffee0
	s_add_i32 s38, s10, 0xfffffee0
	v_writelane_b32 v254, s5, 11
	v_writelane_b32 v254, s1, 12
	s_lshl_b32 s1, s2, 5
	v_writelane_b32 v254, s1, 13
	s_and_b32 s1, s1, 0xffffff80
	v_writelane_b32 v254, s1, 14
	s_lshl_b32 s1, s2, 6
	s_sub_i32 s79, s34, 36
	v_writelane_b32 v254, s1, 15
	s_and_b32 s1, s1, 0xc0
	s_lshl_b64 s[12:13], s[2:3], 14
	s_lshl_b32 s4, s0, 5
	s_cmpk_lt_i32 s2, 0x400
	s_cselect_b64 s[8:9], -1, 0
	s_lshl_b32 s5, s0, 7
	v_writelane_b32 v254, s8, 16
	s_cmp_lt_i32 s0, 0
	s_cselect_b32 s7, s7, s4
	v_writelane_b32 v254, s9, 17
	s_cselect_b32 s9, s91, 0x58
	s_mul_i32 s8, s0, 0x81
	s_mul_i32 s0, s0, s9
	s_cselect_b32 s8, s8, s5
	s_add_i32 s0, s0, s6
	s_mul_hi_i32 s4, s0, 0x2e8ba2e9
	s_lshr_b32 s5, s4, 31
	s_ashr_i32 s4, s4, 4
	s_add_i32 s4, s4, s5
	s_mul_i32 s5, s4, 0x58
	s_sub_i32 s5, s0, s5
	s_bfe_i32 s0, s5, 0x80000
	s_bfe_u32 s0, s0, 0x3000c
	s_add_i32 s9, s5, s0
	s_bfe_i32 s0, s9, 0x80000
	s_and_b32 s9, s9, 0xf8
	s_sub_i32 s5, s5, s9
	s_lshl_b32 s4, s4, 3
	s_sext_i32_i16 s10, s0
	s_sext_i32_i8 s5, s5
	s_add_i32 s14, s4, s5
	s_ashr_i32 s4, s10, 3
	v_writelane_b32 v254, s4, 18
	s_mov_b32 s4, s14
	s_ashr_i32 s15, s14, 31
	v_writelane_b32 v254, s4, 19
	s_lshr_b32 s0, s10, 3
	s_lshl_b32 s93, s34, 5
	v_writelane_b32 v254, s5, 20
	s_lshl_b64 s[4:5], s[14:15], 19
	v_writelane_b32 v254, s4, 21
	s_lshl_b32 s94, s34, 6
	s_mul_hi_i32 s63, s38, 0xc00
	v_writelane_b32 v254, s5, 22
	s_bfe_i64 s[4:5], s[0:1], 0x100000
	s_lshl_b64 s[4:5], s[4:5], 19
	v_writelane_b32 v254, s4, 23
	s_add_i32 s0, s7, s6
	s_mul_i32 s62, s38, 0xc00
	v_writelane_b32 v254, s5, 24
	s_ashr_i32 s4, s0, 31
	s_lshr_b32 s4, s4, 27
	s_add_i32 s4, s0, s4
	s_ashr_i32 s5, s4, 5
	s_and_b32 s4, s4, 0xffe0
	s_sub_i32 s4, s0, s4
	s_bfe_i32 s0, s4, 0x80000
	s_bfe_u32 s0, s0, 0x3000c
	s_add_i32 s7, s4, s0
	s_bfe_i32 s0, s7, 0x80000
	s_and_b32 s7, s7, 0xf8
	s_sub_i32 s4, s4, s7
	s_lshl_b32 s5, s5, 3
	s_sext_i32_i8 s4, s4
	s_add_i32 s10, s5, s4
	s_add_i32 s4, s8, s6
	s_ashr_i32 s5, s4, 31
	s_lshr_b32 s5, s5, 25
	s_add_i32 s5, s4, s5
	s_ashr_i32 s6, s5, 7
	s_and_b32 s5, s5, 0xff80
	s_sub_i32 s5, s4, s5
	s_bfe_i32 s4, s5, 0x80000
	s_bfe_u32 s4, s4, 0x3000c
	s_add_i32 s7, s5, s4
	s_bfe_i32 s4, s7, 0x80000
	s_and_b32 s7, s7, 0xf8
	s_sub_i32 s5, s5, s7
	s_lshl_b32 s6, s6, 3
	s_sext_i32_i16 s8, s4
	s_sext_i32_i8 s5, s5
	s_add_i32 s14, s6, s5
	s_ashr_i32 s5, s8, 3
	v_writelane_b32 v254, s5, 25
	s_mov_b32 s6, s14
	s_ashr_i32 s15, s14, 31
	v_writelane_b32 v254, s6, 26
	s_lshr_b32 s4, s8, 3
	s_bfe_i64 s[4:5], s[4:5], 0x100000
	v_writelane_b32 v254, s7, 27
	s_lshl_b64 s[6:7], s[14:15], 19
	v_writelane_b32 v254, s6, 28
	s_lshl_b64 s[4:5], s[4:5], 19
	s_ashr_i32 s11, s10, 31
	v_writelane_b32 v254, s7, 29
	v_writelane_b32 v254, s4, 30
	s_sext_i32_i16 s9, s0
	s_lshr_b32 s0, s9, 3
	v_writelane_b32 v254, s5, 31
	s_lshl_b64 s[4:5], s[10:11], 19
	v_writelane_b32 v254, s4, 32
	s_ashr_i32 s92, s9, 3
	v_cndmask_b32_e32 v2, v173, v30, vcc
	v_writelane_b32 v254, s5, 33
	s_bfe_i64 s[4:5], s[0:1], 0x100000
	s_lshl_b64 s[6:7], s[4:5], 19
	v_writelane_b32 v254, s6, 34
	s_mov_b32 s0, s10
	s_lshl_b64 s[4:5], s[4:5], 21
	v_writelane_b32 v254, s7, 35
	v_writelane_b32 v254, s0, 36
	s_lshl_b64 s[6:7], s[10:11], 21
	v_cmp_lt_i32_e32 vcc, v29, v0
	v_writelane_b32 v254, s1, 37
	v_writelane_b32 v254, s6, 38
	s_add_u32 s0, s12, 0x4000200
	v_lshlrev_b32_e32 v176, 2, v2
	v_writelane_b32 v254, s7, 39
	v_writelane_b32 v254, s4, 40
	v_cndmask_b32_e32 v2, v173, v29, vcc
	v_cmp_lt_i32_e32 vcc, v28, v0
	v_writelane_b32 v254, s5, 41
	v_writelane_b32 v254, s0, 42
	v_writelane_b32 v254, s12, 43
	s_addc_u32 s0, s13, 0
	s_mov_b32 s4, 0x18800
	v_writelane_b32 v254, s13, 44
	v_writelane_b32 v254, s0, 45
	s_lshl_b32 s0, s2, 7
	s_addk_i32 s0, 0xee00
	v_writelane_b32 v254, s0, 46
	s_lshl_b32 s0, s34, 7
	s_add_i32 s95, s0, 0xffffee00
	s_lshl_b32 s0, s2, 4
	s_addk_i32 s0, 0xfdc0
	v_writelane_b32 v254, s0, 47
	s_addk_i32 s4, 0x120
	v_writelane_b32 v254, s4, 48
	s_mov_b32 s4, 0x14400
	s_addk_i32 s4, 0x120
	v_writelane_b32 v254, s4, 49
	s_lshl_b32 s1, s1, 2
	v_writelane_b32 v254, s1, 50
	v_sub_co_u32_e64 v193, s[4:5], s2, 36
	s_ashr_i32 s39, s38, 31
	s_nop 0
	v_writelane_b32 v254, s4, 51
	s_lshl_b64 s[66:67], s[38:39], 8
	v_lshlrev_b32_e32 v177, 2, v2
	v_writelane_b32 v254, s5, 52
	v_cmp_gt_u32_e64 s[4:5], s90, v193
	v_cndmask_b32_e32 v2, v173, v28, vcc
	v_cmp_lt_i32_e32 vcc, v27, v0
	v_writelane_b32 v254, s4, 53
	v_lshlrev_b32_e32 v178, 2, v2
	v_cndmask_b32_e32 v2, v173, v27, vcc
	v_writelane_b32 v254, s5, 54
	s_lshl_b64 s[4:5], s[34:35], 14
	v_writelane_b32 v254, s4, 55
	v_cmp_lt_i32_e32 vcc, v26, v0
	v_lshlrev_b32_e32 v179, 2, v2
	v_writelane_b32 v254, s5, 56
	s_mov_b64 s[4:5], -1
	v_writelane_b32 v254, s4, 57
	v_cndmask_b32_e32 v2, v173, v26, vcc
	v_cmp_lt_i32_e32 vcc, v1, v0
	v_writelane_b32 v254, s5, 58
	s_mov_b32 s4, s38
	v_writelane_b32 v254, s4, 59
	s_lshl_b32 s0, s34, 4
	v_cndmask_b32_e32 v0, v173, v1, vcc
	v_writelane_b32 v254, s5, 60
	v_writelane_b32 v254, s62, 61
	s_add_i32 s96, s0, 0xfffffdc0
	s_mul_i32 s76, s76, s34
	v_writelane_b32 v254, s63, 62
	v_writelane_b32 v254, s66, 63
	v_lshlrev_b32_e32 v180, 2, v2
	v_lshlrev_b32_e32 v181, 2, v0
	v_writelane_b32 v255, s67, 0
	v_writelane_b32 v255, s84, 1
	s_movk_i32 s78, 0xc00
	s_mov_b32 s97, 0x1fffe0
	v_writelane_b32 v255, s85, 2
	v_writelane_b32 v255, s79, 3
	v_writelane_b32 v255, s92, 4
	v_writelane_b32 v255, s93, 5
	v_writelane_b32 v255, s94, 6
	v_writelane_b32 v255, s95, 7
	s_mov_b32 s44, 0x10000
	v_mov_b32_e32 v161, 0
	s_mov_b32 s45, 0x14000
	s_mov_b32 s46, 0x18000
	s_mov_b32 s47, 0x1c000
	v_mov_b32_e32 v182, 0x358637bd
	s_mov_b32 s50, 0xf800000
	v_mov_b32_e32 v183, 0x260
	s_movk_i32 s0, 0x80
	s_movk_i32 s75, 0x1400
	v_mov_b32_e32 v184, 0x1000
	v_mov_b32_e32 v185, 0x2000
	v_mov_b32_e32 v186, 0xf503000
	v_mov_b32_e32 v187, 1
	s_brev_b32 s30, -2
	s_brev_b32 s64, 18
	s_mov_b32 s74, 0xfe5163ab
	s_mov_b32 s77, 0x3c439041
	s_mov_b32 s82, 0xdb629599
	s_mov_b32 s83, 0xf534ddc0
	v_mov_b32_e32 v188, 0x3c0881c4
	v_mov_b32_e32 v189, 0xbab64f3b
	s_mov_b32 s31, 0x20000
	v_not_b32_e32 v190, 63
	v_not_b32_e32 v191, 31
	v_mov_b32_e32 v192, 0x7fc00000
	v_mov_b32_e32 v194, 0xc00
	v_mov_b32_e32 v195, 0x120
	v_mov_b32_e32 v196, 0x7f800000
	v_mov_b32_e32 v197, 0xff800000
	v_mov_b64_e32 v[162:163], 0xff
	v_mov_b64_e32 v[164:165], 0x100
	v_mov_b64_e32 v[166:167], 0x400
	v_mov_b64_e32 v[168:169], 0x3ff
	s_mov_b32 s33, 0xfc2757d1
	s_mov_b32 s54, 0x4e441529
	s_mov_b32 s55, 0xa2f9836e
	s_mov_b32 s86, 0x3fc90fda
	s_mov_b32 s87, 0x3f22f983
	s_mov_b32 s80, 0xbfc90fda
	s_movk_i32 s81, 0x1f8
	s_mov_b32 s65, 0x49800000
	s_mov_b32 s70, 0
	s_mov_b64 s[88:89], 0x80
	v_writelane_b32 v255, s96, 8
	s_branch .LBB0_108

.LBB0_326:
	s_or_b64 exec, exec, s[10:11]
	s_mov_b64 s[16:17], s[84:85]
	s_waitcnt lgkmcnt(0)
	v_mov_b32_e32 v0, v173
	s_barrier
	s_getreg_b32 s1, hwreg(HW_REG_HW_ID, 0, 7)
	s_and_b32 s1, s1, 63
	s_lshl_b32 s1, s1, 2
	v_mov_b32_e32 v1, s1
	ds_read_b32 v1, v1
	v_readlane_b32 s6, v254, 7
	v_readlane_b32 s7, v254, 8
	s_mov_b64 s[10:11], -1
	s_and_b64 vcc, exec, s[6:7]
	s_waitcnt lgkmcnt(0)
	v_readfirstlane_b32 s1, v1
	s_lshl_b32 s1, s1, 6
	s_and_b32 s1, s1, 0x3fc0
	v_add_u32_e32 v72, s1, v0
	s_cbranch_vccz .LBB0_335
	v_readlane_b32 s6, v254, 51
	v_readlane_b32 s7, v254, 52
	s_andn2_b64 vcc, exec, s[6:7]
	s_cbranch_vccnz .LBB0_334
	v_readfirstlane_b32 s42, v72
	s_cmpk_lt_u32 s42, 0x100
	s_cbranch_scc1 .Ls5_work
	s_load_dwordx2 s[42:43], s[16:17], 0xe0
	s_sub_u32 s48, s2, 32
	s_lshl_b32 s48, s48, 11
	v_and_b32_e32 v140, 0x7f, v72
	v_lshlrev_b32_e32 v140, 4, v140
	v_lshrrev_b32_e32 v141, 7, v72
	v_subrev_u32_e32 v141, 2, v141
	v_lshl_add_u32 v140, v141, 13, v140
	s_waitcnt lgkmcnt(0)
	s_add_u32 s42, s42, s48
	s_addc_u32 s43, s43, 0
	s_add_u32 s42, s42, 0xf100000
	s_addc_u32 s43, s43, 0
	s_movk_i32 s48, 128
.Lpf_s5:
	global_load_dwordx4 v[144:147], v140, s[42:43]
	s_add_u32 s42, s42, 0x4000
	s_addc_u32 s43, s43, 0
	s_sub_u32 s48, s48, 1
	s_cmp_lg_u32 s48, 0
	s_cbranch_scc1 .Lpf_s5
	s_branch .LBB0_334
.Ls5_work:
	s_lshl_b32 s1, s2, 8
	s_addk_i32 s1, 0xe000
	s_load_dwordx4 s[8:11], s[16:17], 0x30
	s_load_dwordx2 s[6:7], s[16:17], 0x40
	v_add_u32_e32 v4, s1, v72
	v_and_b32_e32 v1, 0xffffffc0, v4
	v_lshl_add_u32 v1, s70, 10, v1
	v_and_or_b32 v0, v0, 63, v1
	v_ashrrev_i32_e32 v1, 31, v0
	v_lshlrev_b64 v[0:1], 2, v[0:1]
	s_waitcnt lgkmcnt(0)
	v_lshl_add_u64 v[2:3], s[6:7], 0, v[0:1]
	global_load_dword v5, v[2:3], off
	v_lshl_add_u64 v[2:3], s[10:11], 0, v[0:1]
	global_load_dword v6, v[2:3], off
	v_lshl_add_u64 v[0:1], s[8:9], 0, v[0:1]
	global_load_dword v2, v[0:1], off
	s_waitcnt vmcnt(2)
	v_mul_f32_e32 v0, 0x3fb8aa3b, v5
	v_exp_f32_e32 v3, v0
	s_waitcnt vmcnt(1)
	v_mul_f32_e32 v0, v6, v3
	v_and_b32_e32 v1, 0x7fffffff, v0
	v_cmp_nlt_f32_e64 s[6:7], |v0|, s64
	s_and_saveexec_b64 s[8:9], s[6:7]
	s_xor_b64 s[18:19], exec, s[8:9]
	s_cbranch_execz .LBB0_330
	v_lshrrev_b32_e32 v5, 23, v1
	v_add_u32_e32 v5, 0xffffff88, v5
	v_cmp_lt_u32_e32 vcc, 63, v5
	s_nop 1
	v_cndmask_b32_e32 v6, 0, v190, vcc
	v_add_u32_e32 v5, v6, v5
	v_cmp_lt_u32_e64 s[10:11], 31, v5
	s_nop 1
	v_cndmask_b32_e64 v6, 0, v191, s[10:11]
	v_add_u32_e32 v5, v6, v5
	v_cmp_lt_u32_e64 s[12:13], 31, v5
	s_nop 1
	v_cndmask_b32_e64 v6, 0, v191, s[12:13]
	v_add_u32_e32 v5, v6, v5
	v_and_b32_e32 v6, 0x7fffff, v1
	v_or_b32_e32 v18, 0x800000, v6
	v_mad_u64_u32 v[6:7], s[6:7], v18, s74, 0
	v_mov_b32_e32 v160, v7
	v_mad_u64_u32 v[8:9], s[6:7], v18, s77, v[160:161]
	v_mov_b32_e32 v160, v9
	v_mad_u64_u32 v[10:11], s[6:7], v18, s82, v[160:161]
	v_mov_b32_e32 v160, v11
	v_mad_u64_u32 v[12:13], s[6:7], v18, s83, v[160:161]
	v_mov_b32_e32 v160, v13
	v_mad_u64_u32 v[14:15], s[6:7], v18, s33, v[160:161]
	v_mov_b32_e32 v160, v15
	v_mad_u64_u32 v[16:17], s[6:7], v18, s54, v[160:161]
	v_mov_b32_e32 v160, v17
	v_mad_u64_u32 v[18:19], s[6:7], v18, s55, v[160:161]
	v_cndmask_b32_e32 v7, v16, v12, vcc
	v_cndmask_b32_e32 v9, v18, v14, vcc
	v_cndmask_b32_e32 v13, v19, v16, vcc
	v_cndmask_b32_e64 v11, v9, v7, s[10:11]
	v_cndmask_b32_e64 v9, v13, v9, s[10:11]
	v_cndmask_b32_e32 v13, v14, v10, vcc
	v_cndmask_b32_e64 v7, v7, v13, s[10:11]
	v_sub_u32_e32 v14, 32, v5
	v_cmp_eq_u32_e64 s[14:15], 0, v5
	v_cndmask_b32_e32 v5, v12, v8, vcc
	v_cndmask_b32_e64 v9, v9, v11, s[12:13]
	v_cndmask_b32_e64 v11, v11, v7, s[12:13]
	v_cndmask_b32_e64 v8, v13, v5, s[10:11]
	v_alignbit_b32 v15, v9, v11, v14
	v_cndmask_b32_e64 v7, v7, v8, s[12:13]
	v_cndmask_b32_e64 v9, v15, v9, s[14:15]
	v_alignbit_b32 v12, v11, v7, v14
	v_cndmask_b32_e32 v6, v10, v6, vcc
	v_cndmask_b32_e64 v11, v12, v11, s[14:15]
	v_bfe_u32 v15, v9, 29, 1
	v_cndmask_b32_e64 v5, v5, v6, s[10:11]
	v_alignbit_b32 v12, v9, v11, 30
	v_sub_u32_e32 v16, 0, v15
	v_cndmask_b32_e64 v5, v8, v5, s[12:13]
	v_xor_b32_e32 v12, v12, v16
	v_alignbit_b32 v6, v7, v5, v14
	v_cndmask_b32_e64 v6, v6, v7, s[14:15]
	v_ffbh_u32_e32 v8, v12
	v_alignbit_b32 v7, v11, v6, 30
	v_min_u32_e32 v8, 32, v8
	v_alignbit_b32 v5, v6, v5, 30
	v_xor_b32_e32 v7, v7, v16
	v_sub_u32_e32 v10, 31, v8
	v_xor_b32_e32 v5, v5, v16
	v_alignbit_b32 v11, v12, v7, v10
	v_alignbit_b32 v5, v7, v5, v10
	v_alignbit_b32 v6, v11, v5, 9
	v_ffbh_u32_e32 v7, v6
	v_min_u32_e32 v7, 32, v7
	v_lshrrev_b32_e32 v13, 29, v9
	v_not_b32_e32 v10, v7
	v_alignbit_b32 v5, v6, v5, v10
	v_lshlrev_b32_e32 v6, 31, v13
	v_or_b32_e32 v10, 0x33000000, v6
	v_add_lshl_u32 v7, v7, v8, 23
	v_lshrrev_b32_e32 v5, 9, v5
	v_sub_u32_e32 v7, v10, v7
	v_or_b32_e32 v6, 0.5, v6
	v_lshlrev_b32_e32 v8, 23, v8
	v_or_b32_e32 v5, v7, v5
	v_lshrrev_b32_e32 v7, 9, v11
	v_sub_u32_e32 v6, v6, v8
	v_or_b32_e32 v6, v7, v6
	v_mul_f32_e32 v7, 0x3fc90fda, v6
	v_fma_f32 v8, v6, s86, -v7
	v_fmac_f32_e32 v8, 0x33a22168, v6
	v_fmac_f32_e32 v8, 0x3fc90fda, v5
	v_lshrrev_b32_e32 v6, 30, v9
	v_add_f32_e32 v5, v7, v8
	v_add_u32_e32 v6, v15, v6
